# R3 unit start: counted wait for the q fragments / logits instead of also waiting for the next stage's LDS-DMA loads
# speedup vs baseline: 1.0023x; 1.0001x over previous
.LBB0_1084:
	s_ashr_i32 s52, s3, 7
	s_bfe_u32 s93, s3, 0x20005
	s_lshl_b32 s4, s93, 2
	s_ashr_i32 s53, s52, 31
	s_lshl_b32 s92, s3, 7
	v_mov_b32_e32 v0, s4
	s_lshl_b64 s[54:55], s[52:53], 12
	s_and_b32 s4, s92, 0xf80
	s_or_b32 s4, s54, s4
	s_mov_b32 s5, s55
	s_ashr_i32 s94, s3, 5
	v_lshl_add_u64 v[160:161], s[4:5], 0, v[142:143]
	s_bfe_u32 s95, s3, 0x30002
	s_lshl_b32 s4, s94, 4
	s_or_b32 s4, s4, s95
	global_load_dword v33, v0, s[44:45]
	global_load_dword v32, v0, s[44:45] offset:16
	v_lshlrev_b64 v[0:1], 11, v[160:161]
	s_ashr_i32 s5, s4, 31
	v_lshl_add_u64 v[0:1], s[26:27], 0, v[0:1]
	s_lshl_b32 s42, s93, 9
	s_lshl_b64 s[6:7], s[4:5], 17
	v_lshl_add_u64 v[0:1], v[0:1], 0, s[42:43]
	s_add_u32 s42, s46, s6
	s_addc_u32 s96, s47, s7
	s_or_b32 s4, s4, 8
	s_ashr_i32 s5, s4, 31
	s_lshl_b64 s[4:5], s[4:5], 17
	s_add_u32 s97, s46, s4
	s_addc_u32 s18, s47, s5
	s_add_u32 s6, s42, 0x8000
	s_addc_u32 s7, s96, 0
	s_add_u32 s8, s97, 0x8000
	s_mov_b32 m0, s74
	v_lshl_add_u64 v[28:29], v[0:1], 0, v[144:145]
	s_addc_u32 s9, s18, 0
	v_lshl_add_u64 v[34:35], s[6:7], 0, v[132:133]
	global_load_dwordx4 v[0:3], v[28:29], off
	global_load_dwordx4 v[4:7], v[28:29], off offset:64
	global_load_dwordx4 v[8:11], v[28:29], off offset:128
	global_load_dwordx4 v[12:15], v[28:29], off offset:192
	global_load_dwordx4 v[16:19], v[28:29], off offset:256
	global_load_dwordx4 v[20:23], v[28:29], off offset:320
	global_load_dwordx4 v[24:27], v[28:29], off offset:384
	s_nop 0
	global_load_dwordx4 v[28:31], v[28:29], off offset:448
	s_andn2_b64 vcc, exec, s[0:1]
	global_load_lds_dwordx4 v[34:35], off
	v_lshl_add_u64 v[34:35], s[8:9], 0, v[132:133]
	s_mov_b32 m0, s75
	s_nop 0
	global_load_lds_dwordx4 v[34:35], off
	v_lshl_add_u64 v[34:35], s[6:7], 0, v[134:135]
	s_mov_b32 m0, s76
	s_nop 0
	global_load_lds_dwordx4 v[34:35], off
	v_lshl_add_u64 v[34:35], s[8:9], 0, v[134:135]
	s_mov_b32 m0, s77
	s_nop 0
	global_load_lds_dwordx4 v[34:35], off
	v_lshl_add_u64 v[34:35], s[6:7], 0, v[136:137]
	s_mov_b32 m0, s78
	s_nop 0
	global_load_lds_dwordx4 v[34:35], off
	v_lshl_add_u64 v[34:35], s[8:9], 0, v[136:137]
	s_mov_b32 m0, s79
	s_nop 0
	global_load_lds_dwordx4 v[34:35], off
	v_lshl_add_u64 v[34:35], s[6:7], 0, v[138:139]
	s_mov_b32 m0, s80
	s_nop 0
	global_load_lds_dwordx4 v[34:35], off
	v_lshl_add_u64 v[34:35], s[8:9], 0, v[138:139]
	s_mov_b32 m0, s81
	s_nop 0
	global_load_lds_dwordx4 v[34:35], off
	s_waitcnt vmcnt(8)
	v_cndmask_b32_e64 v34, 0, 1, s[0:1]
	v_cmp_ne_u32_e64 s[4:5], 1, v34
	s_cbranch_vccnz .LBB0_1086
	s_mov_b32 m0, s83
	v_lshl_add_u64 v[36:37], s[6:7], 0, v[140:141]
	v_lshl_add_u64 v[34:35], s[8:9], 0, v[140:141]
	global_load_lds_dwordx4 v[36:37], off
	s_mov_b32 m0, s84
	s_nop 0
	global_load_lds_dwordx4 v[34:35], off
.LBB0_1086:
	v_mul_f32_e32 v34, 0xbfb8aa3b, v33
	v_rndne_f32_e32 v35, v34
	v_sub_f32_e32 v36, v34, v35
	v_fma_f32 v34, v33, s85, -v34
	v_fmac_f32_e32 v34, 0xb2a5705f, v33
	v_add_f32_e32 v34, v36, v34
	v_exp_f32_e32 v34, v34
	v_cvt_i32_f32_e32 v35, v35
	v_cmp_nlt_f32_e32 vcc, s86, v33
	s_add_u32 s58, s42, 0x10000
	s_addc_u32 s59, s96, 0
	v_ldexp_f32 v34, v34, v35
	v_cndmask_b32_e32 v34, 0, v34, vcc
	v_cmp_ngt_f32_e32 vcc, s87, v33
	s_add_u32 s60, s97, 0x10000
	s_addc_u32 s61, s18, 0
	v_cndmask_b32_e32 v79, v224, v34, vcc
	v_add_f32_e32 v159, 1.0, v79
	v_frexp_mant_f32_e32 v33, v159
	v_cmp_gt_f32_e64 s[16:17], s89, v33
	v_mul_f32_e32 v33, 0xbfb8aa3b, v32
	v_rndne_f32_e32 v34, v33
	v_sub_f32_e32 v35, v33, v34
	v_fma_f32 v33, v32, s85, -v33
	v_fmac_f32_e32 v33, 0xb2a5705f, v32
	v_add_f32_e32 v33, v35, v33
	v_exp_f32_e32 v33, v33
	v_cvt_i32_f32_e32 v34, v34
	v_cmp_nlt_f32_e32 vcc, s86, v32
	s_mov_b32 m0, s21
	v_cmp_neq_f32_e64 s[10:11], s88, v79
	v_ldexp_f32 v33, v33, v34
	v_cndmask_b32_e32 v33, 0, v33, vcc
	v_cmp_ngt_f32_e32 vcc, s87, v32
	v_cmp_lt_f32_e64 s[12:13], |v79|, s91
	s_nop 0
	v_cndmask_b32_e32 v78, v224, v33, vcc
	v_add_f32_e32 v162, 1.0, v78
	v_frexp_mant_f32_e32 v32, v162
	v_cmp_gt_f32_e64 s[14:15], s89, v32
	ds_read_b128 v[32:35], v213
	ds_read_b128 v[36:39], v213 offset:34816
	ds_read_b128 v[40:43], v213 offset:64
	ds_read_b128 v[44:47], v213 offset:34880
	s_waitcnt lgkmcnt(0)
	v_mfma_f32_16x16x32_bf16 v[32:35], v[32:35], v[0:3], 0
	v_cmp_neq_f32_e64 s[6:7], s88, v78
	v_cmp_lt_f32_e64 s[8:9], |v78|, s91
	s_and_b64 vcc, exec, s[4:5]
	v_mfma_f32_16x16x32_bf16 v[36:39], v[36:39], v[0:3], 0
	v_mfma_f32_16x16x32_bf16 v[32:35], v[40:43], v[4:7], v[32:35]
	v_mfma_f32_16x16x32_bf16 v[36:39], v[44:47], v[4:7], v[36:39]
	ds_read_b128 v[40:43], v213 offset:128
	ds_read_b128 v[44:47], v213 offset:34944
	s_waitcnt lgkmcnt(1)
	v_mfma_f32_16x16x32_bf16 v[32:35], v[40:43], v[8:11], v[32:35]
	s_waitcnt lgkmcnt(0)
	v_mfma_f32_16x16x32_bf16 v[36:39], v[44:47], v[8:11], v[36:39]
	ds_read_b128 v[40:43], v213 offset:192
	ds_read_b128 v[44:47], v213 offset:35008
	s_waitcnt lgkmcnt(1)
	v_mfma_f32_16x16x32_bf16 v[32:35], v[40:43], v[12:15], v[32:35]
	s_waitcnt lgkmcnt(0)
	v_mfma_f32_16x16x32_bf16 v[36:39], v[44:47], v[12:15], v[36:39]
	ds_read_b128 v[40:43], v213 offset:256
	ds_read_b128 v[44:47], v213 offset:35072
	s_waitcnt lgkmcnt(1)
	v_mfma_f32_16x16x32_bf16 v[32:35], v[40:43], v[16:19], v[32:35]
	s_waitcnt lgkmcnt(0)
	v_mfma_f32_16x16x32_bf16 v[36:39], v[44:47], v[16:19], v[36:39]
	ds_read_b128 v[40:43], v213 offset:320
	ds_read_b128 v[44:47], v213 offset:35136
	s_waitcnt lgkmcnt(1)
	v_mfma_f32_16x16x32_bf16 v[32:35], v[40:43], v[20:23], v[32:35]
	s_waitcnt lgkmcnt(0)
	v_mfma_f32_16x16x32_bf16 v[36:39], v[44:47], v[20:23], v[36:39]
	ds_read_b128 v[40:43], v213 offset:384
	ds_read_b128 v[44:47], v213 offset:35200
	s_waitcnt lgkmcnt(1)
	v_mfma_f32_16x16x32_bf16 v[32:35], v[40:43], v[24:27], v[32:35]
	s_waitcnt lgkmcnt(0)
	v_mfma_f32_16x16x32_bf16 v[36:39], v[44:47], v[24:27], v[36:39]
	ds_read_b128 v[40:43], v213 offset:448
	ds_read_b128 v[44:47], v213 offset:35264
	s_waitcnt lgkmcnt(1)
	v_mfma_f32_16x16x32_bf16 v[32:35], v[40:43], v[28:31], v[32:35]
	s_waitcnt lgkmcnt(0)
	v_mfma_f32_16x16x32_bf16 v[36:39], v[44:47], v[28:31], v[36:39]
	ds_read_b128 v[40:43], v213 offset:8704
	ds_read_b128 v[44:47], v213 offset:43520
	ds_read_b128 v[48:51], v213 offset:8768
	ds_read_b128 v[52:55], v213 offset:43584
	s_waitcnt lgkmcnt(3)
	v_mfma_f32_16x16x32_bf16 v[40:43], v[40:43], v[0:3], 0
	s_waitcnt lgkmcnt(2)
	v_mfma_f32_16x16x32_bf16 v[44:47], v[44:47], v[0:3], 0
	s_waitcnt lgkmcnt(1)
	v_mfma_f32_16x16x32_bf16 v[40:43], v[48:51], v[4:7], v[40:43]
	s_waitcnt lgkmcnt(0)
	v_mfma_f32_16x16x32_bf16 v[44:47], v[52:55], v[4:7], v[44:47]
	ds_read_b128 v[48:51], v213 offset:8832
	ds_read_b128 v[52:55], v213 offset:43648
	s_waitcnt lgkmcnt(1)
	v_mfma_f32_16x16x32_bf16 v[40:43], v[48:51], v[8:11], v[40:43]
	s_waitcnt lgkmcnt(0)
	v_mfma_f32_16x16x32_bf16 v[44:47], v[52:55], v[8:11], v[44:47]
	ds_read_b128 v[48:51], v213 offset:8896
	ds_read_b128 v[52:55], v213 offset:43712
	s_waitcnt lgkmcnt(1)
	v_mfma_f32_16x16x32_bf16 v[40:43], v[48:51], v[12:15], v[40:43]
	s_waitcnt lgkmcnt(0)
	v_mfma_f32_16x16x32_bf16 v[44:47], v[52:55], v[12:15], v[44:47]
	ds_read_b128 v[48:51], v213 offset:8960
	ds_read_b128 v[52:55], v213 offset:43776
	s_waitcnt lgkmcnt(1)
	v_mfma_f32_16x16x32_bf16 v[40:43], v[48:51], v[16:19], v[40:43]
	s_waitcnt lgkmcnt(0)
	v_mfma_f32_16x16x32_bf16 v[44:47], v[52:55], v[16:19], v[44:47]
	ds_read_b128 v[48:51], v213 offset:9024
	ds_read_b128 v[52:55], v213 offset:43840
	s_waitcnt lgkmcnt(1)
	v_mfma_f32_16x16x32_bf16 v[40:43], v[48:51], v[20:23], v[40:43]
	s_waitcnt lgkmcnt(0)
	v_mfma_f32_16x16x32_bf16 v[44:47], v[52:55], v[20:23], v[44:47]
	ds_read_b128 v[48:51], v213 offset:9088
	ds_read_b128 v[52:55], v213 offset:43904
	s_waitcnt lgkmcnt(1)
	v_mfma_f32_16x16x32_bf16 v[40:43], v[48:51], v[24:27], v[40:43]
	s_waitcnt lgkmcnt(0)
	v_mfma_f32_16x16x32_bf16 v[44:47], v[52:55], v[24:27], v[44:47]
	ds_read_b128 v[48:51], v213 offset:9152
	ds_read_b128 v[52:55], v213 offset:43968
	s_waitcnt lgkmcnt(1)
	v_mfma_f32_16x16x32_bf16 v[40:43], v[48:51], v[28:31], v[40:43]
	s_waitcnt lgkmcnt(0)
	v_mfma_f32_16x16x32_bf16 v[44:47], v[52:55], v[28:31], v[44:47]
	ds_read_b128 v[48:51], v213 offset:17408
	ds_read_b128 v[52:55], v213 offset:52224
	ds_read_b128 v[56:59], v213 offset:17472
	ds_read_b128 v[60:63], v213 offset:52288
	s_waitcnt lgkmcnt(3)
	v_mfma_f32_16x16x32_bf16 v[48:51], v[48:51], v[0:3], 0
	s_waitcnt lgkmcnt(2)
	v_mfma_f32_16x16x32_bf16 v[52:55], v[52:55], v[0:3], 0
	s_waitcnt lgkmcnt(1)
	v_mfma_f32_16x16x32_bf16 v[48:51], v[56:59], v[4:7], v[48:51]
	s_waitcnt lgkmcnt(0)
	v_mfma_f32_16x16x32_bf16 v[52:55], v[60:63], v[4:7], v[52:55]
	ds_read_b128 v[56:59], v213 offset:17536
	ds_read_b128 v[60:63], v213 offset:52352
	s_waitcnt lgkmcnt(1)
	v_mfma_f32_16x16x32_bf16 v[48:51], v[56:59], v[8:11], v[48:51]
	s_waitcnt lgkmcnt(0)
	v_mfma_f32_16x16x32_bf16 v[52:55], v[60:63], v[8:11], v[52:55]
	ds_read_b128 v[56:59], v213 offset:17600
	ds_read_b128 v[60:63], v213 offset:52416
	s_waitcnt lgkmcnt(1)
	v_mfma_f32_16x16x32_bf16 v[48:51], v[56:59], v[12:15], v[48:51]
	s_waitcnt lgkmcnt(0)
	v_mfma_f32_16x16x32_bf16 v[52:55], v[60:63], v[12:15], v[52:55]
	ds_read_b128 v[56:59], v213 offset:17664
	ds_read_b128 v[60:63], v213 offset:52480
	s_waitcnt lgkmcnt(1)
	v_mfma_f32_16x16x32_bf16 v[48:51], v[56:59], v[16:19], v[48:51]
	s_waitcnt lgkmcnt(0)
	v_mfma_f32_16x16x32_bf16 v[52:55], v[60:63], v[16:19], v[52:55]
	ds_read_b128 v[56:59], v213 offset:17728
	ds_read_b128 v[60:63], v213 offset:52544
	s_waitcnt lgkmcnt(1)
	v_mfma_f32_16x16x32_bf16 v[48:51], v[56:59], v[20:23], v[48:51]
	s_waitcnt lgkmcnt(0)
	v_mfma_f32_16x16x32_bf16 v[52:55], v[60:63], v[20:23], v[52:55]
	ds_read_b128 v[56:59], v213 offset:17792
	ds_read_b128 v[60:63], v213 offset:52608
	s_waitcnt lgkmcnt(1)
	v_mfma_f32_16x16x32_bf16 v[48:51], v[56:59], v[24:27], v[48:51]
	s_waitcnt lgkmcnt(0)
	v_mfma_f32_16x16x32_bf16 v[52:55], v[60:63], v[24:27], v[52:55]
	ds_read_b128 v[56:59], v213 offset:17856
	ds_read_b128 v[60:63], v213 offset:52672
	s_waitcnt lgkmcnt(1)
	v_mfma_f32_16x16x32_bf16 v[48:51], v[56:59], v[28:31], v[48:51]
	s_waitcnt lgkmcnt(0)
	v_mfma_f32_16x16x32_bf16 v[52:55], v[60:63], v[28:31], v[52:55]
	ds_read_b128 v[56:59], v213 offset:26112
	ds_read_b128 v[60:63], v213 offset:60928
	ds_read_b128 v[64:67], v213 offset:26176
	ds_read_b128 v[68:71], v213 offset:60992
	s_waitcnt lgkmcnt(3)
	v_mfma_f32_16x16x32_bf16 v[56:59], v[56:59], v[0:3], 0
	s_waitcnt lgkmcnt(2)
	v_mfma_f32_16x16x32_bf16 v[60:63], v[60:63], v[0:3], 0
	s_waitcnt lgkmcnt(1)
	v_mfma_f32_16x16x32_bf16 v[56:59], v[64:67], v[4:7], v[56:59]
	s_waitcnt lgkmcnt(0)
	v_mfma_f32_16x16x32_bf16 v[60:63], v[68:71], v[4:7], v[60:63]
	ds_read_b128 v[64:67], v213 offset:26240
	ds_read_b128 v[68:71], v213 offset:61056
	s_waitcnt lgkmcnt(1)
	v_mfma_f32_16x16x32_bf16 v[56:59], v[64:67], v[8:11], v[56:59]
	s_waitcnt lgkmcnt(0)
	v_mfma_f32_16x16x32_bf16 v[60:63], v[68:71], v[8:11], v[60:63]
	ds_read_b128 v[64:67], v213 offset:26304
	ds_read_b128 v[68:71], v213 offset:61120
	s_waitcnt lgkmcnt(1)
	v_mfma_f32_16x16x32_bf16 v[56:59], v[64:67], v[12:15], v[56:59]
	s_waitcnt lgkmcnt(0)
	v_mfma_f32_16x16x32_bf16 v[60:63], v[68:71], v[12:15], v[60:63]
	ds_read_b128 v[64:67], v213 offset:26368
	ds_read_b128 v[68:71], v213 offset:61184
	s_waitcnt lgkmcnt(1)
	v_mfma_f32_16x16x32_bf16 v[56:59], v[64:67], v[16:19], v[56:59]
	s_waitcnt lgkmcnt(0)
	v_mfma_f32_16x16x32_bf16 v[60:63], v[68:71], v[16:19], v[60:63]
	ds_read_b128 v[64:67], v213 offset:26432
	ds_read_b128 v[68:71], v213 offset:61248
	s_waitcnt lgkmcnt(1)
	v_mfma_f32_16x16x32_bf16 v[56:59], v[64:67], v[20:23], v[56:59]
	s_waitcnt lgkmcnt(0)
	v_mfma_f32_16x16x32_bf16 v[60:63], v[68:71], v[20:23], v[60:63]
	ds_read_b128 v[64:67], v213 offset:26496
	ds_read_b128 v[68:71], v213 offset:61312
	s_waitcnt lgkmcnt(1)
	v_mfma_f32_16x16x32_bf16 v[56:59], v[64:67], v[24:27], v[56:59]
	s_waitcnt lgkmcnt(0)
	v_mfma_f32_16x16x32_bf16 v[60:63], v[68:71], v[24:27], v[60:63]
	ds_read_b128 v[64:67], v213 offset:26560
	ds_read_b128 v[68:71], v213 offset:61376
	s_waitcnt vmcnt(0)
	s_waitcnt lgkmcnt(1)
	v_mfma_f32_16x16x32_bf16 v[56:59], v[64:67], v[28:31], v[56:59]
	v_lshl_add_u64 v[64:65], s[58:59], 0, v[132:133]
	s_waitcnt lgkmcnt(0)
	s_barrier
	global_load_lds_dwordx4 v[64:65], off
	v_lshl_add_u64 v[64:65], s[60:61], 0, v[132:133]
	s_mov_b32 m0, s48
	v_mfma_f32_16x16x32_bf16 v[60:63], v[68:71], v[28:31], v[60:63]
	global_load_lds_dwordx4 v[64:65], off
	v_lshl_add_u64 v[64:65], s[58:59], 0, v[134:135]
	s_mov_b32 m0, s49
	s_nop 0
	global_load_lds_dwordx4 v[64:65], off
	v_lshl_add_u64 v[64:65], s[60:61], 0, v[134:135]
	s_mov_b32 m0, s62
	s_nop 0
	global_load_lds_dwordx4 v[64:65], off
	v_lshl_add_u64 v[64:65], s[58:59], 0, v[136:137]
	s_mov_b32 m0, s63
	s_nop 0
	global_load_lds_dwordx4 v[64:65], off
	v_lshl_add_u64 v[64:65], s[60:61], 0, v[136:137]
	s_mov_b32 m0, s64
	s_nop 0
	global_load_lds_dwordx4 v[64:65], off
	v_lshl_add_u64 v[64:65], s[58:59], 0, v[138:139]
	s_mov_b32 m0, s65
	s_nop 0
	global_load_lds_dwordx4 v[64:65], off
	v_lshl_add_u64 v[64:65], s[60:61], 0, v[138:139]
	s_mov_b32 m0, s66
	s_nop 0
	global_load_lds_dwordx4 v[64:65], off
	s_cbranch_vccnz .LBB0_1088
	s_mov_b32 m0, s82
	v_lshl_add_u64 v[66:67], s[58:59], 0, v[140:141]
	v_lshl_add_u64 v[64:65], s[60:61], 0, v[140:141]
	global_load_lds_dwordx4 v[66:67], off
	s_add_i32 m0, s82, 0x8800
	s_nop 0
	global_load_lds_dwordx4 v[64:65], off
